# MLA: mid-tile barrier of waves 4-7 moved to right after the QK MFMAs
# baseline (speedup 1.0000x reference)
; #define MFMA32(a, b, c) __builtin_amdgcn_mfma_f32_32x32x16_bf16((a), (b), (c), 0, 0, 0)
; #define VFRAG(dst, kk_) do { _Pragma("unroll") for (int mt = 0; mt < 4; ++mt) dst[mt] = *(const LAS bf16x8*)(vb + (32 * mt + r32) * VP + 16 * (kk_) + 8 * hf); } while (0)
; #define KFRAG(da, dc, ks_) do { da = *(const LAS bf16x8*)(kb + r32 * KP + 16 * (ks_) + 8 * hf); dc = *(const LAS bf16x8*)(kb + (32 + r32) * KP + 16 * (ks_) + 8 * hf); } while (0)
; DI void mla_attn_phase(LAS unsigned char* lds, const bf16_t* Qg, const bf16_t* Kg, const bf16_t* Vtg, bf16_t* MIX) {
;     ...
;                     bf16x8 ka0, kc0_, ka1, kc1_;
;                     KFRAG(ka0, kc0_, 0); KFRAG(ka1, kc1_, 1);
;                     __builtin_amdgcn_sched_barrier(0);
;                     f32x16 s0, s1;
; #pragma unroll
;                     for (int i = 0; i < 16; ++i) { s0[i] = 0.f; s1[i] = 0.f; }
;                     s0 = MFMA32(ka0, qf[0], s0); s1 = MFMA32(kc0_, qf[0], s1); KFRAG(ka0, kc0_, 2); __builtin_amdgcn_sched_barrier(0);
;                     s0 = MFMA32(ka1, qf[1], s0); s1 = MFMA32(kc1_, qf[1], s1); KFRAG(ka1, kc1_, 3); __builtin_amdgcn_sched_barrier(0);
;                     s0 = MFMA32(ka0, qf[2], s0); s1 = MFMA32(kc0_, qf[2], s1); KFRAG(ka0, kc0_, 4); __builtin_amdgcn_sched_barrier(0);
;                     s0 = MFMA32(ka1, qf[3], s0); s1 = MFMA32(kc1_, qf[3], s1); KFRAG(ka1, kc1_, 5); __builtin_amdgcn_sched_barrier(0);
;                     s0 = MFMA32(ka0, qf[4], s0); s1 = MFMA32(kc0_, qf[4], s1); s0 = MFMA32(ka1, qf[5], s0); s1 = MFMA32(kc1_, qf[5], s1);
;     ...
;                     bf16x8 vfa[4], vfb[4];
;                     VFRAG(vfa, 0); VFRAG(vfb, 1);
;                     __builtin_amdgcn_sched_barrier(0);
.LBB0_361:
	s_cmp_gt_i32 s40, s39
	s_cbranch_scc1 .Lmla_skipall
	s_lshl_b32 s30, s41, 15
	s_add_i32 s30, s30, 0
	v_lshlrev_b32_e32 v0, 1, v166
	v_add_u32_e32 v1, s30, v0
	v_add_u32_e32 v3, v1, v230
	ds_read_b128 v[4:7], v3
	ds_read_b128 v[8:11], v3 offset:32
	ds_read_b128 v[12:15], v3 offset:6656
	ds_read_b128 v[136:139], v3 offset:6688
	s_waitcnt lgkmcnt(0)
	v_mfma_f32_32x32x16_bf16 v[80:95], v[4:7], v[112:115], 0
	ds_read_b128 v[4:7], v3 offset:64
	ds_read_b128 v[140:143], v3 offset:6720
	v_mfma_f32_32x32x16_bf16 v[80:95], v[8:11], v[116:119], v[80:95]
	ds_read_b128 v[8:11], v3 offset:96
	ds_read_b128 v[144:147], v3 offset:6752
	s_waitcnt lgkmcnt(0)
	v_mfma_f32_32x32x16_bf16 v[80:95], v[4:7], v[120:123], v[80:95]
	ds_read_b128 v[4:7], v3 offset:128
	ds_read_b128 v[148:151], v3 offset:6784
	v_mfma_f32_32x32x16_bf16 v[80:95], v[8:11], v[124:127], v[80:95]
	ds_read_b128 v[8:11], v3 offset:160
	ds_read_b128 v[236:239], v3 offset:6816
	v_mfma_f32_32x32x16_bf16 v[96:111], v[12:15], v[112:115], 0
	v_add_u32_e32 v1, v1, v232
	v_mfma_f32_32x32x16_bf16 v[96:111], v[136:139], v[116:119], v[96:111]
	v_mfma_f32_32x32x16_bf16 v[96:111], v[140:143], v[120:123], v[96:111]
	v_mfma_f32_32x32x16_bf16 v[96:111], v[144:147], v[124:127], v[96:111]
	ds_read_b128 v[144:147], v1 offset:13312
	ds_read_b128 v[140:143], v1 offset:17920
	s_waitcnt lgkmcnt(2)
	v_mfma_f32_32x32x16_bf16 v[80:95], v[4:7], v[128:131], v[80:95]
	v_mfma_f32_32x32x16_bf16 v[96:111], v[148:151], v[128:131], v[96:111]
	ds_read_b128 v[148:151], v1 offset:22528
	ds_read_b128 v[152:155], v1 offset:27136
	v_add3_u32 v1, s30, v232, v0
	v_mfma_f32_32x32x16_bf16 v[80:95], v[8:11], v[132:135], v[80:95]
	ds_read_b128 v[136:139], v1 offset:13344
	ds_read_b128 v[12:15], v1 offset:17952
	ds_read_b128 v[4:7], v1 offset:22560
	ds_read_b128 v[8:11], v1 offset:27168
	v_mfma_f32_32x32x16_bf16 v[96:111], v[236:239], v[132:135], v[96:111]
	s_cmp_lt_u32 s34, 0x80
	s_cbranch_scc1 .Lmla_bd1
	s_and_b64 vcc, exec, s[28:29]
	s_cbranch_vccnz .Lmla_bw1
	s_waitcnt vmcnt(4)
	s_branch .Lmla_bb1

; DI int crow(int r, int hi) { return (r & 3) + 8 * (r >> 2) + 4 * hi; }
; DI void mla_attn_phase(LAS unsigned char* lds, const bf16_t* Qg, const bf16_t* Kg, const bf16_t* Vtg, bf16_t* MIX) {
;     ...
;                     if (kt >= 4 * qb) { const int qpos = q0 + r32;
; #pragma unroll
;                         for (int i = 0; i < 16; ++i) { const int key0 = 64 * kt + crow(i, hf); if (key0 > qpos) s0[i] = -INFINITY; if (key0 + 32 > qpos) s1[i] = -INFINITY; } }
.Lmla_bd1:
	s_cmp_lt_i32 s42, s8
	s_cbranch_scc1 .LBB0_364
	v_add_u32_e32 v0, s40, v231
	v_add_u32_e32 v3, 32, v0
	v_cmp_le_i32_e32 vcc, v3, v167
	v_add_u32_e32 v3, 33, v0
	s_nop 5
	v_cndmask_b32_e32 v96, v229, v96, vcc
	v_cmp_lt_i32_e32 vcc, v0, v167
	s_nop 1
	v_cndmask_b32_e32 v81, v229, v81, vcc
	v_cmp_le_i32_e32 vcc, v0, v167
	s_nop 1
	v_cndmask_b32_e32 v80, v229, v80, vcc
	v_cmp_le_i32_e32 vcc, v3, v167
	v_add_u32_e32 v3, 2, v0
	s_nop 0
	v_cndmask_b32_e32 v97, v229, v97, vcc
	v_cmp_le_i32_e32 vcc, v3, v167
	v_add_u32_e32 v3, 34, v0
	s_nop 0
	v_cndmask_b32_e32 v82, v229, v82, vcc
	v_cmp_le_i32_e32 vcc, v3, v167
	v_add_u32_e32 v3, 3, v0
	s_nop 0
	v_cndmask_b32_e32 v98, v229, v98, vcc
	v_cmp_le_i32_e32 vcc, v3, v167
	v_add_u32_e32 v3, 35, v0
	s_nop 0
	v_cndmask_b32_e32 v83, v229, v83, vcc
	v_cmp_le_i32_e32 vcc, v3, v167
	v_add_u32_e32 v3, 8, v0
	s_nop 0
	v_cndmask_b32_e32 v99, v229, v99, vcc
	v_cmp_le_i32_e32 vcc, v3, v167
	v_add_u32_e32 v3, 40, v0
	s_nop 0
	v_cndmask_b32_e32 v84, v229, v84, vcc
	v_cmp_le_i32_e32 vcc, v3, v167
	v_add_u32_e32 v3, 9, v0
	s_nop 0
	v_cndmask_b32_e32 v100, v229, v100, vcc
	v_cmp_le_i32_e32 vcc, v3, v167
	v_add_u32_e32 v3, 41, v0
	s_nop 0
	v_cndmask_b32_e32 v85, v229, v85, vcc
	v_cmp_le_i32_e32 vcc, v3, v167
	v_add_u32_e32 v3, 10, v0
	s_nop 0
	v_cndmask_b32_e32 v101, v229, v101, vcc
	v_cmp_le_i32_e32 vcc, v3, v167
	v_add_u32_e32 v3, 42, v0
	s_nop 0
	v_cndmask_b32_e32 v86, v229, v86, vcc
	v_cmp_le_i32_e32 vcc, v3, v167
	v_add_u32_e32 v3, 11, v0
	s_nop 0
	v_cndmask_b32_e32 v102, v229, v102, vcc
	v_cmp_le_i32_e32 vcc, v3, v167
	v_add_u32_e32 v3, 43, v0
	s_nop 0
	v_cndmask_b32_e32 v87, v229, v87, vcc
	v_cmp_le_i32_e32 vcc, v3, v167
	v_add_u32_e32 v3, 16, v0
	s_nop 0
	v_cndmask_b32_e32 v103, v229, v103, vcc
	v_cmp_le_i32_e32 vcc, v3, v167
	v_add_u32_e32 v3, 48, v0
	s_nop 0
	v_cndmask_b32_e32 v88, v229, v88, vcc
	v_cmp_le_i32_e32 vcc, v3, v167
	v_add_u32_e32 v3, 17, v0
	s_nop 0
	v_cndmask_b32_e32 v104, v229, v104, vcc
	v_cmp_le_i32_e32 vcc, v3, v167
	v_add_u32_e32 v3, 49, v0
	s_nop 0
	v_cndmask_b32_e32 v89, v229, v89, vcc
	v_cmp_le_i32_e32 vcc, v3, v167
	v_add_u32_e32 v3, 18, v0
	s_nop 0
	v_cndmask_b32_e32 v105, v229, v105, vcc
	v_cmp_le_i32_e32 vcc, v3, v167
	v_add_u32_e32 v3, 50, v0
	s_nop 0
	v_cndmask_b32_e32 v90, v229, v90, vcc
	v_cmp_le_i32_e32 vcc, v3, v167
	v_add_u32_e32 v3, 19, v0
	s_nop 0
	v_cndmask_b32_e32 v106, v229, v106, vcc
	v_cmp_le_i32_e32 vcc, v3, v167
	v_add_u32_e32 v3, 51, v0
	s_nop 0
	v_cndmask_b32_e32 v91, v229, v91, vcc
	v_cmp_le_i32_e32 vcc, v3, v167
	v_add_u32_e32 v3, 24, v0
	s_nop 0
	v_cndmask_b32_e32 v107, v229, v107, vcc
	v_cmp_le_i32_e32 vcc, v3, v167
	v_add_u32_e32 v3, 56, v0
	s_nop 0
	v_cndmask_b32_e32 v92, v229, v92, vcc
	v_cmp_le_i32_e32 vcc, v3, v167
	v_add_u32_e32 v3, 25, v0
	s_nop 0
	v_cndmask_b32_e32 v108, v229, v108, vcc
	v_cmp_le_i32_e32 vcc, v3, v167
	v_add_u32_e32 v3, 57, v0
	s_nop 0
	v_cndmask_b32_e32 v93, v229, v93, vcc
	v_cmp_le_i32_e32 vcc, v3, v167
	v_add_u32_e32 v3, 26, v0
	s_nop 0
	v_cndmask_b32_e32 v109, v229, v109, vcc
	v_cmp_le_i32_e32 vcc, v3, v167
	v_add_u32_e32 v3, 58, v0
	s_nop 0
	v_cndmask_b32_e32 v94, v229, v94, vcc
	v_cmp_le_i32_e32 vcc, v3, v167
	v_add_u32_e32 v3, 27, v0
	v_add_u32_e32 v0, 59, v0
	v_cndmask_b32_e32 v110, v229, v110, vcc
	v_cmp_le_i32_e32 vcc, v3, v167
	s_nop 1
	v_cndmask_b32_e32 v95, v229, v95, vcc
	v_cmp_le_i32_e32 vcc, v0, v167
	s_nop 1
	v_cndmask_b32_e32 v111, v229, v111, vcc

; DI unsigned pk2(float lo, float hi) { const f32x2_t v = {lo, hi}; const bf16x2_t b = __builtin_convertvector(v, bf16x2_t); return __builtin_bit_cast(unsigned, b); }
; DI void mla_attn_phase(LAS unsigned char* lds, const bf16_t* Qg, const bf16_t* Kg, const bf16_t* Vtg, bf16_t* MIX) {
;     ...
;                     const float m_new = fmaxf(m_run, mx), alpha = __builtin_amdgcn_exp2f(m_run - m_new); m_run = m_new;
;                     float sum = 0.f;
; #pragma unroll
;                     for (int i = 0; i < 16; ++i) { s0[i] = __builtin_amdgcn_exp2f(s0[i] - m_new); s1[i] = __builtin_amdgcn_exp2f(s1[i] - m_new); sum += s0[i] + s1[i]; }
;                     l_run = l_run * alpha + sum;
;                     if (__any(alpha != 1.f)) {
; #pragma unroll
;                         for (int mt = 0; mt < 4; ++mt)
; #pragma unroll
;                             for (int i = 0; i < 16; ++i) o[mt][i] *= alpha; }
;                     bf16x8 pf[4];
; #pragma unroll
;                     for (int sp = 0; sp < 2; ++sp) { u32x4 p0, p1;
; #pragma unroll
;                         for (int j = 0; j < 4; ++j) { p0[j] = pk2(s0[8 * sp + 2 * j], s0[8 * sp + 2 * j + 1]); p1[j] = pk2(s1[8 * sp + 2 * j], s1[8 * sp + 2 * j + 1]); }
;                         pf[sp] = __builtin_bit_cast(bf16x8, p0); pf[2 + sp] = __builtin_bit_cast(bf16x8, p1); }
;                     __builtin_amdgcn_sched_barrier(0);
;                     MLA_PV();
.Lmla_mid:
	v_sub_f32_e32 v80, v80, v3
	v_sub_f32_e32 v96, v96, v3
	v_exp_f32_e32 v80, v80
	v_exp_f32_e32 v96, v96
	v_sub_f32_e32 v81, v81, v3
	v_sub_f32_e32 v97, v97, v3
	v_exp_f32_e32 v81, v81
	v_exp_f32_e32 v97, v97
	v_sub_f32_e32 v82, v82, v3
	v_sub_f32_e32 v98, v98, v3
	v_exp_f32_e32 v82, v82
	v_exp_f32_e32 v98, v98
	v_sub_f32_e32 v83, v83, v3
	v_sub_f32_e32 v99, v99, v3
	v_exp_f32_e32 v83, v83
	v_exp_f32_e32 v99, v99
	v_add_f32_e32 v218, v80, v96
	v_sub_f32_e32 v84, v84, v3
	v_add_f32_e32 v218, 0, v218
	v_add_f32_e32 v219, v81, v97
	v_exp_f32_e32 v226, v84
	v_sub_f32_e32 v84, v100, v3
	v_add_f32_e32 v218, v219, v218
	v_add_f32_e32 v219, v82, v98
	v_exp_f32_e32 v100, v84
	v_sub_f32_e32 v84, v85, v3
	v_add_f32_e32 v218, v219, v218
	v_add_f32_e32 v219, v83, v99
	v_exp_f32_e32 v227, v84
	v_sub_f32_e32 v84, v101, v3
	v_sub_f32_e32 v86, v86, v3
	v_exp_f32_e32 v101, v84
	v_add_f32_e32 v84, v219, v218
	v_exp_f32_e32 v218, v86
	v_sub_f32_e32 v86, v102, v3
	v_exp_f32_e32 v102, v86
	v_sub_f32_e32 v86, v87, v3
	v_exp_f32_e32 v87, v86
	v_sub_f32_e32 v86, v103, v3
	v_exp_f32_e32 v103, v86
	v_sub_f32_e32 v86, v88, v3
	v_exp_f32_e32 v88, v86
	v_sub_f32_e32 v86, v104, v3
	v_exp_f32_e32 v104, v86
	v_sub_f32_e32 v86, v89, v3
	v_exp_f32_e32 v89, v86
	v_sub_f32_e32 v86, v105, v3
	v_exp_f32_e32 v105, v86
	v_sub_f32_e32 v86, v90, v3
	v_exp_f32_e32 v90, v86
	v_sub_f32_e32 v86, v106, v3
	v_exp_f32_e32 v106, v86
	v_sub_f32_e32 v86, v91, v3
	v_exp_f32_e32 v91, v86
	v_sub_f32_e32 v86, v107, v3
	v_exp_f32_e32 v107, v86
	v_sub_f32_e32 v86, v92, v3
	v_add_f32_e32 v85, v226, v100
	v_exp_f32_e32 v219, v86
	v_sub_f32_e32 v86, v108, v3
	v_add_f32_e32 v84, v85, v84
	v_add_f32_e32 v85, v227, v101
	v_exp_f32_e32 v108, v86
	v_sub_f32_e32 v86, v93, v3
	v_add_f32_e32 v84, v85, v84
	v_add_f32_e32 v85, v218, v102
	v_exp_f32_e32 v234, v86
	v_sub_f32_e32 v86, v109, v3
	v_add_f32_e32 v84, v85, v84
	v_add_f32_e32 v85, v87, v103
	v_exp_f32_e32 v109, v86
	v_sub_f32_e32 v86, v94, v3
	v_add_f32_e32 v84, v85, v84
	v_add_f32_e32 v85, v88, v104
	v_exp_f32_e32 v235, v86
	v_sub_f32_e32 v86, v110, v3
	v_add_f32_e32 v84, v85, v84
	v_add_f32_e32 v85, v89, v105
	v_exp_f32_e32 v110, v86
	v_sub_f32_e32 v86, v95, v3
	v_add_f32_e32 v84, v85, v84
	v_add_f32_e32 v85, v90, v106
	v_exp_f32_e32 v95, v86
	v_sub_f32_e32 v86, v111, v3
	v_add_f32_e32 v84, v85, v84
	v_add_f32_e32 v85, v91, v107
	v_exp_f32_e32 v111, v86
	v_add_f32_e32 v84, v85, v84
	v_add_f32_e32 v85, v219, v108
	v_add_f32_e32 v84, v85, v84
	v_add_f32_e32 v85, v234, v109
	v_add_f32_e32 v84, v85, v84
	v_add_f32_e32 v85, v235, v110
	v_add_f32_e32 v84, v85, v84
	v_add_f32_e32 v85, v95, v111
	v_add_f32_e32 v236, v85, v84
	v_fmac_f32_e32 v236, v233, v0
	v_cvt_pk_bf16_f32 v80, v80, v81
	v_cvt_pk_bf16_f32 v84, v96, v97
	v_cvt_pk_bf16_f32 v81, v82, v83
	v_cvt_pk_bf16_f32 v85, v98, v99
	v_cvt_pk_bf16_f32 v82, v226, v227
	v_cvt_pk_bf16_f32 v86, v100, v101
	v_cvt_pk_bf16_f32 v83, v218, v87
	v_cvt_pk_bf16_f32 v87, v102, v103
	v_cvt_pk_bf16_f32 v88, v88, v89
	v_cvt_pk_bf16_f32 v92, v104, v105
	v_cvt_pk_bf16_f32 v89, v90, v91
	v_cvt_pk_bf16_f32 v93, v106, v107
	v_cvt_pk_bf16_f32 v90, v219, v234
	v_cvt_pk_bf16_f32 v94, v108, v109
	v_cvt_pk_bf16_f32 v91, v235, v95
	v_cvt_pk_bf16_f32 v95, v110, v111
	s_waitcnt lgkmcnt(6)
	v_mfma_f32_32x32x16_bf16 v[64:79], v[144:147], v[80:83], v[64:79]
	v_mfma_f32_32x32x16_bf16 v[48:63], v[140:143], v[80:83], v[48:63]
	s_waitcnt lgkmcnt(0)
	v_mfma_f32_32x32x16_bf16 v[32:47], v[148:151], v[80:83], v[32:47]
	v_mfma_f32_32x32x16_bf16 v[16:31], v[152:155], v[80:83], v[16:31]
	ds_read_b128 v[80:83], v1 offset:13376
	ds_read_b128 v[96:99], v1 offset:17984
	ds_read_b128 v[100:103], v1 offset:22592
	ds_read_b128 v[104:107], v1 offset:27200
	v_mfma_f32_32x32x16_bf16 v[64:79], v[136:139], v[88:91], v[64:79]
	v_mfma_f32_32x32x16_bf16 v[48:63], v[12:15], v[88:91], v[48:63]
	v_mfma_f32_32x32x16_bf16 v[32:47], v[4:7], v[88:91], v[32:47]
	v_mfma_f32_32x32x16_bf16 v[16:31], v[8:11], v[88:91], v[16:31]
	ds_read_b128 v[4:7], v1 offset:13408
	ds_read_b128 v[8:11], v1 offset:18016
	ds_read_b128 v[12:15], v1 offset:22624
	ds_read_b128 v[88:91], v1 offset:27232
	s_waitcnt lgkmcnt(4)
	v_mfma_f32_32x32x16_bf16 v[64:79], v[80:83], v[84:87], v[64:79]
	v_mov_b32_e32 v233, v236
	v_mfma_f32_32x32x16_bf16 v[48:63], v[96:99], v[84:87], v[48:63]
	v_mfma_f32_32x32x16_bf16 v[32:47], v[100:103], v[84:87], v[32:47]
	v_mfma_f32_32x32x16_bf16 v[16:31], v[104:107], v[84:87], v[16:31]
	s_waitcnt lgkmcnt(0)
	v_mfma_f32_32x32x16_bf16 v[64:79], v[4:7], v[92:95], v[64:79]
	v_mfma_f32_32x32x16_bf16 v[48:63], v[8:11], v[92:95], v[48:63]
	v_mfma_f32_32x32x16_bf16 v[32:47], v[12:15], v[92:95], v[32:47]
	v_mfma_f32_32x32x16_bf16 v[16:31], v[88:91], v[92:95], v[16:31]
	s_branch .Lmla_tail
